# attention: tile-0 row-sum adds moved into the second QK block's MFMA gaps, padding nops between max3 dropped
# speedup vs baseline: 1.0051x; 1.0051x over previous
.LBB0_531:
	s_waitcnt lgkmcnt(0)
	v_mfma_f32_32x32x16_bf16 v[98:113], v[150:153], v[114:117], v[98:113]
	v_mbcnt_hi_u32_b32 v210, -1, v1
	v_xor_b32_e32 v209, 32, v210
	v_mfma_f32_32x32x16_bf16 v[82:97], v[4:7], v[114:117], v[82:97]
	v_mfma_f32_32x32x16_bf16 v[98:113], v[154:157], v[118:121], v[98:113]
	v_mfma_f32_32x32x16_bf16 v[82:97], v[8:11], v[118:121], v[82:97]
	v_mfma_f32_32x32x16_bf16 v[98:113], v[158:161], v[122:125], v[98:113]
	v_mfma_f32_32x32x16_bf16 v[82:97], v[12:15], v[122:125], v[82:97]
	v_mfma_f32_32x32x16_bf16 v[98:113], v[162:165], v[126:129], v[98:113]
	v_mfma_f32_32x32x16_bf16 v[82:97], v[146:149], v[126:129], v[82:97]
	.Lattn_q0_join:
	s_nop 15
	s_nop 7
	s_nop 0
	v_max3_f32 v16, v98, v99, v100
	v_max3_f32 v166, v82, v83, v84
	v_max3_f32 v16, v16, v101, v102
	v_max3_f32 v166, v166, v85, v86
	v_max3_f32 v16, v16, v103, v104
	v_max3_f32 v166, v166, v87, v88
	v_max3_f32 v16, v16, v105, v106
	v_max3_f32 v166, v166, v89, v90
	v_max3_f32 v16, v16, v107, v108
	v_max3_f32 v166, v166, v91, v92
	v_max3_f32 v16, v16, v109, v110
	v_max3_f32 v166, v166, v93, v94
	v_max3_f32 v16, v16, v111, v112
	v_max3_f32 v166, v166, v95, v96
	v_max3_f32 v16, v16, v166, v113
	v_and_b32_e32 v166, 64, v210
	v_add_u32_e32 v211, 64, v166
	v_cmp_lt_i32_e32 vcc, v209, v211
	v_max3_f32 v16, v16, v97, v16
	s_nop 1
	v_cndmask_b32_e32 v166, v210, v209, vcc
	v_lshlrev_b32_e32 v212, 2, v166
	ds_bpermute_b32 v166, v212, v16
	s_waitcnt lgkmcnt(0)
	v_max3_f32 v166, v16, v166, v16
	s_nop 0
	v_pk_add_f32 v[188:189], v[186:187], v[166:167]
	s_nop 0
	v_cmp_gt_f32_e32 vcc, v188, v189
	s_cbranch_vccz .LBB0_533
	s_nop 0
	v_cndmask_b32_e32 v166, v187, v188, vcc
	v_sub_f32_e32 v16, v187, v166
	v_exp_f32_e32 v16, v16
	v_mov_b32_e32 v187, v166
	v_mul_f32_e32 v207, v207, v16
	v_pk_mul_f32 v[80:81], v[80:81], v[16:17] op_sel_hi:[1,0]
	v_pk_mul_f32 v[78:79], v[78:79], v[16:17] op_sel_hi:[1,0]
	v_pk_mul_f32 v[76:77], v[76:77], v[16:17] op_sel_hi:[1,0]
	v_pk_mul_f32 v[74:75], v[74:75], v[16:17] op_sel_hi:[1,0]
	v_pk_mul_f32 v[72:73], v[72:73], v[16:17] op_sel_hi:[1,0]
	v_pk_mul_f32 v[70:71], v[70:71], v[16:17] op_sel_hi:[1,0]
	v_pk_mul_f32 v[68:69], v[68:69], v[16:17] op_sel_hi:[1,0]
	v_pk_mul_f32 v[66:67], v[66:67], v[16:17] op_sel_hi:[1,0]
	v_pk_mul_f32 v[64:65], v[64:65], v[16:17] op_sel_hi:[1,0]
	v_pk_mul_f32 v[62:63], v[62:63], v[16:17] op_sel_hi:[1,0]
	v_pk_mul_f32 v[60:61], v[60:61], v[16:17] op_sel_hi:[1,0]
	v_pk_mul_f32 v[58:59], v[58:59], v[16:17] op_sel_hi:[1,0]
	v_pk_mul_f32 v[56:57], v[56:57], v[16:17] op_sel_hi:[1,0]
	v_pk_mul_f32 v[54:55], v[54:55], v[16:17] op_sel_hi:[1,0]
	v_pk_mul_f32 v[52:53], v[52:53], v[16:17] op_sel_hi:[1,0]
	v_pk_mul_f32 v[50:51], v[50:51], v[16:17] op_sel_hi:[1,0]

.LBB0_539:
	s_andn2_b64 vcc, exec, s[74:75]
	v_mov_b32_e32 v16, 0
	s_cbranch_vccnz .LBB0_541
	s_add_i32 s6, s5, 0
	s_add_i32 s6, s6, 0x20400
	v_mov_b32_e32 v16, s6
	ds_read_b32 v16, v16
	v_mfma_f32_32x32x16_bf16 v[98:113], v[150:153], v[130:133], 0
	v_add_f32_e32 v207, v207, v186
	v_add_f32_e32 v207, v207, v188
	v_add_f32_e32 v207, v207, v189
	v_add_f32_e32 v207, v207, v213
	v_add_f32_e32 v207, v207, v214
	s_nop 0
	v_mfma_f32_32x32x16_bf16 v[82:97], v[4:7], v[130:133], 0
	v_add_f32_e32 v207, v207, v215
	v_add_f32_e32 v207, v207, v216
	v_add_f32_e32 v207, v207, v217
	v_add_f32_e32 v207, v207, v218
	v_add_f32_e32 v207, v207, v219
	v_mfma_f32_32x32x16_bf16 v[98:113], v[154:157], v[134:137], v[98:113]
	v_add_f32_e32 v207, v207, v220
	v_add_f32_e32 v207, v207, v221
	v_add_f32_e32 v207, v207, v222
	v_add_f32_e32 v207, v207, v223
	v_add_f32_e32 v207, v207, v224
	v_mfma_f32_32x32x16_bf16 v[82:97], v[8:11], v[134:137], v[82:97]
	v_add_f32_e32 v207, v207, v225
	v_add_f32_e32 v207, v207, v226
	v_add_f32_e32 v207, v207, v227
	v_add_f32_e32 v207, v207, v228
	v_add_f32_e32 v207, v207, v229
	v_mfma_f32_32x32x16_bf16 v[98:113], v[158:161], v[138:141], v[98:113]
	v_add_f32_e32 v207, v207, v230
	v_add_f32_e32 v207, v207, v231
	v_add_f32_e32 v207, v207, v232
	v_add_f32_e32 v207, v207, v233
	v_mfma_f32_32x32x16_bf16 v[82:97], v[12:15], v[138:141], v[82:97]
	v_add_f32_e32 v207, v207, v234
	v_add_f32_e32 v207, v207, v235
	v_add_f32_e32 v207, v207, v236
	v_add_f32_e32 v207, v207, v237
	v_mfma_f32_32x32x16_bf16 v[98:113], v[162:165], v[142:145], v[98:113]
	v_add_f32_e32 v207, v207, v238
	v_add_f32_e32 v207, v207, v239
	v_add_f32_e32 v207, v207, v240
	v_add_f32_e32 v207, v207, v241
	v_mfma_f32_32x32x16_bf16 v[82:97], v[146:149], v[142:145], v[82:97]
	s_branch .Lattn_q1_join
.LBB0_541:
	v_mfma_f32_32x32x16_bf16 v[98:113], v[150:153], v[130:133], v[98:113]
	v_add_f32_e32 v207, v207, v186
	v_add_f32_e32 v207, v207, v188
	v_add_f32_e32 v207, v207, v189
	v_add_f32_e32 v207, v207, v213
	v_add_f32_e32 v207, v207, v214
	s_nop 0
	v_mfma_f32_32x32x16_bf16 v[82:97], v[4:7], v[130:133], v[82:97]
	v_add_f32_e32 v207, v207, v215
	v_add_f32_e32 v207, v207, v216
	v_add_f32_e32 v207, v207, v217
	v_add_f32_e32 v207, v207, v218
	v_add_f32_e32 v207, v207, v219
	v_mfma_f32_32x32x16_bf16 v[98:113], v[154:157], v[134:137], v[98:113]
	v_add_f32_e32 v207, v207, v220
	v_add_f32_e32 v207, v207, v221
	v_add_f32_e32 v207, v207, v222
	v_add_f32_e32 v207, v207, v223
	v_add_f32_e32 v207, v207, v224
	v_mfma_f32_32x32x16_bf16 v[82:97], v[8:11], v[134:137], v[82:97]
	v_add_f32_e32 v207, v207, v225
	v_add_f32_e32 v207, v207, v226
	v_add_f32_e32 v207, v207, v227
	v_add_f32_e32 v207, v207, v228
	v_add_f32_e32 v207, v207, v229
	v_mfma_f32_32x32x16_bf16 v[98:113], v[158:161], v[138:141], v[98:113]
	v_add_f32_e32 v207, v207, v230
	v_add_f32_e32 v207, v207, v231
	v_add_f32_e32 v207, v207, v232
	v_add_f32_e32 v207, v207, v233
	v_mfma_f32_32x32x16_bf16 v[82:97], v[12:15], v[138:141], v[82:97]
	v_add_f32_e32 v207, v207, v234
	v_add_f32_e32 v207, v207, v235
	v_add_f32_e32 v207, v207, v236
	v_add_f32_e32 v207, v207, v237
	v_mfma_f32_32x32x16_bf16 v[98:113], v[162:165], v[142:145], v[98:113]
	v_add_f32_e32 v207, v207, v238
	v_add_f32_e32 v207, v207, v239
	v_add_f32_e32 v207, v207, v240
	v_add_f32_e32 v207, v207, v241
	v_mfma_f32_32x32x16_bf16 v[82:97], v[146:149], v[142:145], v[82:97]
	.Lattn_q1_join:
	s_nop 15
	s_nop 7
	s_nop 0
	v_max3_f32 v4, v98, v99, v100
	v_max3_f32 v5, v82, v83, v84
	v_max3_f32 v4, v4, v101, v102
	v_max3_f32 v5, v5, v85, v86
	v_max3_f32 v4, v4, v103, v104
	v_max3_f32 v5, v5, v87, v88
	v_max3_f32 v4, v4, v105, v106
	v_max3_f32 v5, v5, v89, v90
	v_max3_f32 v4, v4, v107, v108
	v_max3_f32 v5, v5, v91, v92
	v_max3_f32 v4, v4, v109, v110
	v_max3_f32 v5, v5, v93, v94
	v_max3_f32 v4, v4, v111, v112
	v_max3_f32 v5, v5, v95, v96
	v_max3_f32 v4, v4, v5, v113
	v_max3_f32 v4, v4, v97, v4
	ds_bpermute_b32 v5, v212, v4
	s_waitcnt lgkmcnt(0)
	v_max3_f32 v166, v4, v5, v4
	s_nop 0
	v_pk_add_f32 v[4:5], v[16:17], v[166:167]
	s_nop 0
	v_cmp_gt_f32_e32 vcc, v4, v5
	s_cbranch_vccz .LBB0_543
	s_nop 0
	v_cndmask_b32_e32 v5, v17, v4, vcc
	v_sub_f32_e32 v4, v17, v5
	v_exp_f32_e32 v4, v4
	v_mov_b32_e32 v17, v5
	v_mul_f32_e32 v2, v2, v4
	v_pk_mul_f32 v[48:49], v[48:49], v[4:5] op_sel_hi:[1,0]
	v_pk_mul_f32 v[46:47], v[46:47], v[4:5] op_sel_hi:[1,0]
	v_pk_mul_f32 v[44:45], v[44:45], v[4:5] op_sel_hi:[1,0]
	v_pk_mul_f32 v[42:43], v[42:43], v[4:5] op_sel_hi:[1,0]
	v_pk_mul_f32 v[40:41], v[40:41], v[4:5] op_sel_hi:[1,0]
	v_pk_mul_f32 v[38:39], v[38:39], v[4:5] op_sel_hi:[1,0]
	v_pk_mul_f32 v[36:37], v[36:37], v[4:5] op_sel_hi:[1,0]
	v_pk_mul_f32 v[34:35], v[34:35], v[4:5] op_sel_hi:[1,0]
	v_pk_mul_f32 v[32:33], v[32:33], v[4:5] op_sel_hi:[1,0]
	v_pk_mul_f32 v[30:31], v[30:31], v[4:5] op_sel_hi:[1,0]
	v_pk_mul_f32 v[28:29], v[28:29], v[4:5] op_sel_hi:[1,0]
	v_pk_mul_f32 v[26:27], v[26:27], v[4:5] op_sel_hi:[1,0]
	v_pk_mul_f32 v[24:25], v[24:25], v[4:5] op_sel_hi:[1,0]
	v_pk_mul_f32 v[22:23], v[22:23], v[4:5] op_sel_hi:[1,0]
	v_pk_mul_f32 v[20:21], v[20:21], v[4:5] op_sel_hi:[1,0]
	v_pk_mul_f32 v[18:19], v[18:19], v[4:5] op_sel_hi:[1,0]
.LBB0_543:
	v_sub_f32_e32 v4, v17, v16
	v_sub_f32_e32 v5, v98, v4
	v_exp_f32_e32 v5, v5
	v_sub_f32_e32 v7, v99, v4
	v_exp_f32_e32 v7, v7
	v_sub_f32_e32 v8, v100, v4
	v_exp_f32_e32 v8, v8
	v_sub_f32_e32 v9, v101, v4
	v_exp_f32_e32 v9, v9
	v_sub_f32_e32 v10, v102, v4
	v_add_f32_e32 v6, 0, v5
	v_exp_f32_e32 v10, v10
	v_sub_f32_e32 v11, v103, v4
	v_add_f32_e32 v6, v7, v6
	v_exp_f32_e32 v11, v11
	v_sub_f32_e32 v12, v104, v4
	v_add_f32_e32 v6, v8, v6
	v_exp_f32_e32 v12, v12
	v_sub_f32_e32 v13, v105, v4
	v_add_f32_e32 v6, v9, v6
	v_exp_f32_e32 v13, v13
	v_sub_f32_e32 v14, v106, v4
	v_add_f32_e32 v6, v10, v6
	v_exp_f32_e32 v14, v14
	v_sub_f32_e32 v15, v107, v4
	v_add_f32_e32 v6, v11, v6
	v_exp_f32_e32 v15, v15
	v_sub_f32_e32 v16, v108, v4
	v_add_f32_e32 v6, v12, v6
	v_exp_f32_e32 v16, v16
	v_sub_f32_e32 v98, v109, v4
	v_add_f32_e32 v6, v13, v6
	v_exp_f32_e32 v98, v98
	v_sub_f32_e32 v99, v110, v4
	v_add_f32_e32 v6, v14, v6
	v_exp_f32_e32 v99, v99
	v_sub_f32_e32 v100, v111, v4
	v_add_f32_e32 v6, v15, v6
	v_exp_f32_e32 v100, v100
	v_sub_f32_e32 v101, v112, v4
	v_add_f32_e32 v6, v16, v6
	v_exp_f32_e32 v101, v101
	v_sub_f32_e32 v102, v113, v4
	v_add_f32_e32 v6, v98, v6
	v_exp_f32_e32 v102, v102
	v_sub_f32_e32 v82, v82, v4
	v_add_f32_e32 v6, v99, v6
	v_exp_f32_e32 v103, v82
	v_sub_f32_e32 v82, v83, v4
	v_add_f32_e32 v6, v100, v6
	v_exp_f32_e32 v104, v82
	v_sub_f32_e32 v82, v84, v4
	v_add_f32_e32 v6, v101, v6
	v_exp_f32_e32 v105, v82
	v_sub_f32_e32 v82, v85, v4
	v_add_f32_e32 v6, v102, v6
	v_exp_f32_e32 v106, v82
	v_sub_f32_e32 v82, v86, v4
	v_add_f32_e32 v6, v103, v6
	v_exp_f32_e32 v107, v82
	v_sub_f32_e32 v82, v87, v4
	v_add_f32_e32 v6, v104, v6
	v_exp_f32_e32 v108, v82
	v_sub_f32_e32 v82, v88, v4
	v_add_f32_e32 v6, v105, v6
	v_exp_f32_e32 v109, v82
	v_sub_f32_e32 v82, v89, v4
	v_add_f32_e32 v6, v106, v6
	v_exp_f32_e32 v110, v82
	v_sub_f32_e32 v82, v90, v4
	v_add_f32_e32 v6, v107, v6
	v_exp_f32_e32 v90, v82
	v_sub_f32_e32 v82, v91, v4
	v_add_f32_e32 v6, v108, v6
	v_exp_f32_e32 v91, v82
	v_sub_f32_e32 v82, v92, v4
	v_add_f32_e32 v6, v109, v6
	v_exp_f32_e32 v92, v82
	v_sub_f32_e32 v82, v93, v4
	v_add_f32_e32 v6, v110, v6
	v_exp_f32_e32 v93, v82
	v_sub_f32_e32 v82, v94, v4
	v_add_f32_e32 v6, v90, v6
	v_exp_f32_e32 v94, v82
	v_sub_f32_e32 v82, v95, v4
	v_add_f32_e32 v6, v91, v6
	v_exp_f32_e32 v95, v82
	v_sub_f32_e32 v82, v96, v4
	v_add_f32_e32 v6, v92, v6
	v_exp_f32_e32 v96, v82
	v_sub_f32_e32 v4, v97, v4
	v_add_f32_e32 v6, v93, v6
	v_exp_f32_e32 v97, v4
	v_add_f32_e32 v6, v94, v6
	v_add_f32_e32 v6, v95, v6
	v_add_f32_e32 v6, v96, v6
	v_add_f32_e32 v4, v97, v6
	v_add_f32_e32 v2, v2, v4
	v_cvt_pk_bf16_f32 v4, v90, v91
	ds_read_b64_tr_b16 v[90:91], v200 offset:0
	v_cvt_pk_bf16_f32 v82, v5, v7
	v_cvt_pk_bf16_f32 v5, v92, v93
	ds_read_b64_tr_b16 v[92:93], v200 offset:1024
	v_cvt_pk_bf16_f32 v6, v94, v95
	ds_read_b64_tr_b16 v[94:95], v200 offset:2048
	v_cvt_pk_bf16_f32 v7, v96, v97
	ds_read_b64_tr_b16 v[96:97], v200 offset:3072
	v_cvt_pk_bf16_f32 v87, v16, v98
	v_cvt_pk_bf16_f32 v88, v99, v100
	ds_read_b64_tr_b16 v[98:99], v200 offset:4096
	v_cvt_pk_bf16_f32 v89, v101, v102
	ds_read_b64_tr_b16 v[100:101], v200 offset:5120
	v_cvt_pk_bf16_f32 v83, v8, v9
	v_cvt_pk_bf16_f32 v8, v103, v104
	ds_read_b64_tr_b16 v[102:103], v200 offset:6144
	v_cvt_pk_bf16_f32 v9, v105, v106
	ds_read_b64_tr_b16 v[104:105], v200 offset:7168
	v_cvt_pk_bf16_f32 v84, v10, v11
	v_cvt_pk_bf16_f32 v10, v107, v108
	ds_read_b64_tr_b16 v[106:107], v201 offset:0
	v_cvt_pk_bf16_f32 v11, v109, v110
	ds_read_b64_tr_b16 v[108:109], v201 offset:1024
	ds_read_b64_tr_b16 v[110:111], v201 offset:2048
	ds_read_b64_tr_b16 v[112:113], v201 offset:3072
	ds_read_b64_tr_b16 v[146:147], v201 offset:4096
	ds_read_b64_tr_b16 v[148:149], v201 offset:5120
	v_cvt_pk_bf16_f32 v85, v12, v13
	ds_read_b64_tr_b16 v[12:13], v201 offset:6144
	v_cvt_pk_bf16_f32 v86, v14, v15
	ds_read_b64_tr_b16 v[14:15], v201 offset:7168
	v_add_u32_e32 v208, 0xffffff00, v208
	s_waitcnt lgkmcnt(0)
	s_add_i32 s89, s89, 64
	v_mfma_f32_32x32x16_bf16 v[34:49], v[90:93], v[82:85], v[34:49]
	s_andn2_b64 vcc, exec, s[12:13]
	v_mfma_f32_32x32x16_bf16 v[18:33], v[106:109], v[82:85], v[18:33]
	v_mfma_f32_32x32x16_bf16 v[34:49], v[94:97], v[86:89], v[34:49]
	v_mfma_f32_32x32x16_bf16 v[18:33], v[110:113], v[86:89], v[18:33]
	v_mfma_f32_32x32x16_bf16 v[34:49], v[98:101], v[8:11], v[34:49]
	v_mfma_f32_32x32x16_bf16 v[18:33], v[146:149], v[8:11], v[18:33]
	v_mfma_f32_32x32x16_bf16 v[34:49], v[102:105], v[4:7], v[34:49]
	v_mfma_f32_32x32x16_bf16 v[18:33], v[12:15], v[4:7], v[18:33]
	s_cbranch_vccz .LBB0_545
	s_mov_b32 s33, s11
	s_branch .LBB0_525
